# combination: permlane32_swap max exchange (17 sites) + DPP row-sum in OUT epilogue + early K-fragment LDS reads with counted waits + E5 compressed-branch priority 0 + OUT epilogue counted vmcnt waits
# speedup vs baseline: 1.0033x; 1.0033x over previous
.LBB0_506:
	s_or_b64 exec, exec, s[2:3]
	s_mulk_i32 s16, 0x4800
	v_cmp_lt_i32_e32 vcc, 1, v34
	s_and_saveexec_b64 s[2:3], vcc
	s_xor_b64 s[22:23], exec, s[2:3]
	s_cbranch_execz .LBB0_516
	v_cmp_lt_i32_e32 vcc, 2, v34
	s_and_saveexec_b64 s[2:3], vcc
	s_xor_b64 s[2:3], exec, s[2:3]
	s_cbranch_execz .LBB0_511
	v_add3_u32 v124, s16, v100, v116
	s_setprio 1
	ds_read_b128 v[34:37], v124
	ds_read_b128 v[38:41], v124 offset:16
	ds_read_b128 v[42:45], v124 offset:32
	ds_read_b128 v[46:49], v124 offset:48
	v_cmp_lt_i32_e32 vcc, v211, v210
	s_waitcnt lgkmcnt(3)
	v_mfma_f32_32x32x16_bf16 v[50:65], v[34:37], v[78:81], 0
	ds_read_b128 v[34:37], v124 offset:4608
	ds_read_b128 v[120:123], v124 offset:4624
	ds_read_b128 v[126:129], v124 offset:4640
	ds_read_b128 v[130:133], v124 offset:4656
	s_waitcnt lgkmcnt(6)
	v_mfma_f32_32x32x16_bf16 v[50:65], v[38:41], v[74:77], v[50:65]
	s_waitcnt lgkmcnt(5)
	v_mfma_f32_32x32x16_bf16 v[50:65], v[42:45], v[70:73], v[50:65]
	s_waitcnt lgkmcnt(4)
	v_mfma_f32_32x32x16_bf16 v[50:65], v[46:49], v[66:69], v[50:65]
	s_waitcnt lgkmcnt(3)
	v_mfma_f32_32x32x16_bf16 v[34:49], v[34:37], v[78:81], 0
	s_waitcnt lgkmcnt(2)
	v_mfma_f32_32x32x16_bf16 v[34:49], v[120:123], v[74:77], v[34:49]
	s_waitcnt lgkmcnt(1)
	v_mfma_f32_32x32x16_bf16 v[34:49], v[126:129], v[70:73], v[34:49]
	s_waitcnt lgkmcnt(0)
	v_mfma_f32_32x32x16_bf16 v[34:49], v[130:133], v[66:69], v[34:49]
	s_nop 1
	v_max3_f32 v120, v50, s85, v51
	v_max3_f32 v120, v120, v52, v53
	v_max3_f32 v120, v120, v54, v55
	v_max3_f32 v120, v120, v56, v57
	v_max3_f32 v120, v120, v58, v59
	v_max3_f32 v120, v120, v60, v61
	v_max3_f32 v120, v120, v62, v63
	v_max3_f32 v120, v120, v64, v65
	s_nop 1
	v_max3_f32 v120, v120, v34, v35
	v_max3_f32 v120, v120, v36, v37
	v_max3_f32 v120, v120, v38, v39
	v_max3_f32 v120, v120, v40, v41
	v_max3_f32 v120, v120, v42, v43
	v_max3_f32 v120, v120, v44, v45
	v_max3_f32 v120, v120, v46, v47
	v_cndmask_b32_e32 v121, v209, v211, vcc
	v_max3_f32 v120, v120, v48, v49
	v_mov_b32_e32 v121, v120
	s_nop 1
	v_permlane32_swap_b32_e32 v121, v120
	v_max_f32_e32 v120, v120, v121
	v_mul_f32_e32 v120, 0x3e38aa3b, v120
	v_cndmask_b32_e64 v120, v220, v120, s[74:75]
	v_add_f32_e32 v121, 0x40c00000, v119
	v_cmp_gt_f32_e32 vcc, v120, v121
	s_cbranch_vccz .LBB0_510
	s_nop 0
	v_cndmask_b32_e32 v121, v119, v120, vcc
	v_sub_f32_e32 v119, v119, v121
	v_exp_f32_e32 v119, v119
	s_nop 0
	v_cndmask_b32_e32 v120, 1.0, v119, vcc
	v_mul_f32_e32 v117, v117, v120
	v_pk_mul_f32 v[32:33], v[32:33], v[120:121] op_sel_hi:[1,0]
	v_pk_mul_f32 v[30:31], v[30:31], v[120:121] op_sel_hi:[1,0]
	v_pk_mul_f32 v[28:29], v[28:29], v[120:121] op_sel_hi:[1,0]
	v_pk_mul_f32 v[26:27], v[26:27], v[120:121] op_sel_hi:[1,0]
	v_pk_mul_f32 v[24:25], v[24:25], v[120:121] op_sel_hi:[1,0]
	v_pk_mul_f32 v[22:23], v[22:23], v[120:121] op_sel_hi:[1,0]
	v_pk_mul_f32 v[20:21], v[20:21], v[120:121] op_sel_hi:[1,0]
	v_pk_mul_f32 v[18:19], v[18:19], v[120:121] op_sel_hi:[1,0]
	v_pk_mul_f32 v[16:17], v[16:17], v[120:121] op_sel_hi:[1,0]
	v_pk_mul_f32 v[14:15], v[14:15], v[120:121] op_sel_hi:[1,0]
	v_pk_mul_f32 v[12:13], v[12:13], v[120:121] op_sel_hi:[1,0]
	v_pk_mul_f32 v[10:11], v[10:11], v[120:121] op_sel_hi:[1,0]
	v_pk_mul_f32 v[8:9], v[8:9], v[120:121] op_sel_hi:[1,0]
	v_pk_mul_f32 v[6:7], v[6:7], v[120:121] op_sel_hi:[1,0]
	v_pk_mul_f32 v[4:5], v[4:5], v[120:121] op_sel_hi:[1,0]
	v_pk_mul_f32 v[2:3], v[2:3], v[120:121] op_sel_hi:[1,0]
	v_mov_b32_e32 v119, v121

.LBB0_511:
	s_andn2_saveexec_b64 s[2:3], s[2:3]
	s_cbranch_execz .LBB0_515
	v_add3_u32 v124, s16, v100, v116
	s_setprio 1
	ds_read_b128 v[34:37], v124
	ds_read_b128 v[50:53], v124 offset:16
	ds_read_b128 v[54:57], v124 offset:32
	ds_read_b128 v[58:61], v124 offset:48
	v_cmp_lt_i32_e32 vcc, -1, v118
	s_waitcnt lgkmcnt(3)
	v_mfma_f32_32x32x16_bf16 v[34:49], v[34:37], v[78:81], 0
	v_cmp_gt_i32_e64 s[38:39], 1, v118
	v_cmp_gt_i32_e64 s[40:41], 32, v118
	v_cmp_gt_i32_e64 s[42:43], 33, v118
	v_cmp_gt_i32_e64 s[44:45], 34, v118
	v_cmp_gt_i32_e64 s[46:47], 35, v118
	v_cmp_gt_i32_e64 s[48:49], 36, v118
	v_cmp_gt_i32_e64 s[50:51], 37, v118
	s_waitcnt lgkmcnt(2)
	v_mfma_f32_32x32x16_bf16 v[34:49], v[50:53], v[74:77], v[34:49]
	ds_read_b128 v[50:53], v124 offset:4608
	ds_read_b128 v[120:123], v124 offset:4624
	ds_read_b128 v[126:129], v124 offset:4640
	ds_read_b128 v[130:133], v124 offset:4656
	v_cmp_gt_i32_e64 s[52:53], 38, v118
	v_cmp_gt_i32_e64 s[56:57], 39, v118
	v_cmp_gt_i32_e64 s[58:59], 48, v118
	v_cmp_gt_i32_e64 s[60:61], 49, v118
	v_cmp_gt_i32_e64 s[62:63], 50, v118
	s_waitcnt lgkmcnt(5)
	v_mfma_f32_32x32x16_bf16 v[34:49], v[54:57], v[70:73], v[34:49]
	v_cmp_gt_i32_e64 s[64:65], 51, v118
	v_cmp_gt_i32_e64 s[66:67], 52, v118
	v_cmp_gt_i32_e64 s[68:69], 53, v118
	v_cmp_gt_i32_e64 s[70:71], 54, v118
	v_cmp_gt_i32_e64 s[54:55], 55, v118
	s_waitcnt lgkmcnt(4)
	v_mfma_f32_32x32x16_bf16 v[34:49], v[58:61], v[66:69], v[34:49]
	s_waitcnt lgkmcnt(3)
	v_mfma_f32_32x32x16_bf16 v[50:65], v[50:53], v[78:81], 0
	s_waitcnt lgkmcnt(2)
	v_mfma_f32_32x32x16_bf16 v[50:65], v[120:123], v[74:77], v[50:65]
	s_waitcnt lgkmcnt(1)
	v_mfma_f32_32x32x16_bf16 v[50:65], v[126:129], v[70:73], v[50:65]
	s_waitcnt lgkmcnt(0)
	v_mfma_f32_32x32x16_bf16 v[50:65], v[130:133], v[66:69], v[50:65]
	s_nop 1
	v_cndmask_b32_e32 v122, v220, v34, vcc
	v_cmp_lt_i32_e32 vcc, 1, v118
	v_cndmask_b32_e64 v120, v35, v220, s[38:39]
	v_max3_f32 v35, v122, s85, v120
	v_cndmask_b32_e32 v36, v220, v36, vcc
	v_cmp_lt_i32_e32 vcc, 2, v118
	s_nop 3
	v_cndmask_b32_e64 v123, v50, v220, s[40:41]
	v_cndmask_b32_e32 v37, v220, v37, vcc
	v_cmp_lt_i32_e32 vcc, 3, v118
	v_max3_f32 v35, v35, v36, v37
	v_cndmask_b32_e64 v124, v51, v220, s[42:43]
	v_cndmask_b32_e32 v121, v220, v38, vcc
	v_cmp_lt_i32_e32 vcc, 4, v118
	v_cndmask_b32_e64 v125, v52, v220, s[44:45]
	v_cndmask_b32_e64 v126, v53, v220, s[46:47]
	v_cndmask_b32_e32 v38, v220, v39, vcc
	v_cmp_lt_i32_e32 vcc, 5, v118
	v_max3_f32 v35, v35, v121, v38
	v_cndmask_b32_e64 v127, v54, v220, s[48:49]
	v_cndmask_b32_e32 v39, v220, v40, vcc
	v_cmp_lt_i32_e32 vcc, 6, v118
	v_cndmask_b32_e64 v128, v55, v220, s[50:51]
	v_cndmask_b32_e64 v130, v56, v220, s[52:53]
	v_cndmask_b32_e32 v40, v220, v41, vcc
	v_cmp_lt_i32_e32 vcc, 15, v118
	v_max3_f32 v35, v35, v39, v40
	v_cndmask_b32_e64 v131, v57, v220, s[56:57]
	v_cndmask_b32_e32 v42, v220, v42, vcc
	v_cmp_lt_i32_e32 vcc, 16, v118
	v_cndmask_b32_e64 v132, v58, v220, s[58:59]
	v_cndmask_b32_e64 v133, v59, v220, s[60:61]
	v_cndmask_b32_e32 v41, v220, v43, vcc
	v_cmp_lt_i32_e32 vcc, 17, v118
	v_max3_f32 v35, v35, v42, v41
	v_cndmask_b32_e64 v134, v60, v220, s[62:63]
	v_cndmask_b32_e32 v43, v220, v44, vcc
	v_cmp_lt_i32_e32 vcc, 18, v118
	v_cndmask_b32_e64 v135, v61, v220, s[64:65]
	v_cndmask_b32_e64 v136, v62, v220, s[66:67]
	v_cndmask_b32_e32 v44, v220, v45, vcc
	v_cmp_lt_i32_e32 vcc, 19, v118
	v_max3_f32 v35, v35, v43, v44
	v_cndmask_b32_e64 v137, v63, v220, s[68:69]
	v_cndmask_b32_e32 v45, v220, v46, vcc
	v_cmp_lt_i32_e32 vcc, 20, v118
	v_cndmask_b32_e64 v129, v64, v220, s[70:71]
	s_nop 0
	v_cndmask_b32_e32 v46, v220, v47, vcc
	v_cmp_lt_i32_e32 vcc, 21, v118
	v_max3_f32 v35, v35, v45, v46
	s_nop 0
	v_cndmask_b32_e32 v47, v220, v48, vcc
	v_cmp_lt_i32_e32 vcc, 22, v118
	s_nop 1
	v_cndmask_b32_e32 v48, v220, v49, vcc
	v_max3_f32 v35, v35, v47, v48
	v_max3_f32 v35, v35, v123, v124
	v_max3_f32 v35, v35, v125, v126
	v_max3_f32 v35, v35, v127, v128
	v_max3_f32 v35, v35, v130, v131
	v_max3_f32 v35, v35, v132, v133
	v_max3_f32 v35, v35, v134, v135
	v_max3_f32 v138, v35, v136, v137
	v_cndmask_b32_e64 v35, v65, v220, s[54:55]
	v_cmp_lt_i32_e32 vcc, v211, v210
	v_max3_f32 v65, v138, v129, v35
	s_nop 0
	v_cndmask_b32_e32 v138, v209, v211, vcc
	v_mov_b32_e32 v138, v65
	s_nop 1
	v_permlane32_swap_b32_e32 v138, v65
	v_max_f32_e32 v65, v65, v138
	v_mul_f32_e32 v65, 0x3e38aa3b, v65
	v_add_f32_e32 v138, 0x40c00000, v119
	v_cmp_gt_f32_e32 vcc, v65, v138
	s_cbranch_vccz .LBB0_514
	s_nop 0
	v_cndmask_b32_e32 v65, v119, v65, vcc
	v_sub_f32_e32 v119, v119, v65
	v_exp_f32_e32 v119, v119
	s_nop 0
	v_cndmask_b32_e32 v138, 1.0, v119, vcc
	v_mul_f32_e32 v117, v117, v138
	v_pk_mul_f32 v[32:33], v[32:33], v[138:139] op_sel_hi:[1,0]
	v_pk_mul_f32 v[30:31], v[30:31], v[138:139] op_sel_hi:[1,0]
	v_pk_mul_f32 v[28:29], v[28:29], v[138:139] op_sel_hi:[1,0]
	v_pk_mul_f32 v[26:27], v[26:27], v[138:139] op_sel_hi:[1,0]
	v_pk_mul_f32 v[24:25], v[24:25], v[138:139] op_sel_hi:[1,0]
	v_pk_mul_f32 v[22:23], v[22:23], v[138:139] op_sel_hi:[1,0]
	v_pk_mul_f32 v[20:21], v[20:21], v[138:139] op_sel_hi:[1,0]
	v_pk_mul_f32 v[18:19], v[18:19], v[138:139] op_sel_hi:[1,0]
	v_pk_mul_f32 v[16:17], v[16:17], v[138:139] op_sel_hi:[1,0]
	v_pk_mul_f32 v[14:15], v[14:15], v[138:139] op_sel_hi:[1,0]
	v_pk_mul_f32 v[12:13], v[12:13], v[138:139] op_sel_hi:[1,0]
	v_pk_mul_f32 v[10:11], v[10:11], v[138:139] op_sel_hi:[1,0]
	v_pk_mul_f32 v[8:9], v[8:9], v[138:139] op_sel_hi:[1,0]
	v_pk_mul_f32 v[6:7], v[6:7], v[138:139] op_sel_hi:[1,0]
	v_pk_mul_f32 v[4:5], v[4:5], v[138:139] op_sel_hi:[1,0]
	v_pk_mul_f32 v[2:3], v[2:3], v[138:139] op_sel_hi:[1,0]
	v_mov_b32_e32 v119, v65

.LBB0_516:
	s_andn2_saveexec_b64 s[22:23], s[22:23]
	s_cbranch_execz .LBB0_522
	v_cmp_eq_u32_e32 vcc, 1, v34
	s_and_saveexec_b64 s[2:3], vcc
	s_cbranch_execz .LBB0_521
	v_add3_u32 v124, s16, v100, v116
	s_setprio 1
	ds_read_b128 v[34:37], v124
	ds_read_b128 v[38:41], v124 offset:16
	ds_read_b128 v[42:45], v124 offset:32
	ds_read_b128 v[46:49], v124 offset:48
	v_cmp_lt_i32_e32 vcc, v211, v210
	s_waitcnt lgkmcnt(3)
	v_mfma_f32_32x32x16_bf16 v[50:65], v[34:37], v[78:81], 0
	ds_read_b128 v[34:37], v124 offset:4608
	ds_read_b128 v[120:123], v124 offset:4624
	ds_read_b128 v[126:129], v124 offset:4640
	ds_read_b128 v[130:133], v124 offset:4656
	s_waitcnt lgkmcnt(6)
	v_mfma_f32_32x32x16_bf16 v[50:65], v[38:41], v[74:77], v[50:65]
	s_waitcnt lgkmcnt(5)
	v_mfma_f32_32x32x16_bf16 v[50:65], v[42:45], v[70:73], v[50:65]
	s_waitcnt lgkmcnt(4)
	v_mfma_f32_32x32x16_bf16 v[50:65], v[46:49], v[66:69], v[50:65]
	s_waitcnt lgkmcnt(3)
	v_mfma_f32_32x32x16_bf16 v[34:49], v[34:37], v[78:81], 0
	s_waitcnt lgkmcnt(2)
	v_mfma_f32_32x32x16_bf16 v[34:49], v[120:123], v[74:77], v[34:49]
	s_waitcnt lgkmcnt(1)
	v_mfma_f32_32x32x16_bf16 v[34:49], v[126:129], v[70:73], v[34:49]
	s_waitcnt lgkmcnt(0)
	v_mfma_f32_32x32x16_bf16 v[34:49], v[130:133], v[66:69], v[34:49]
	s_nop 1
	v_max3_f32 v120, v50, s85, v51
	v_max3_f32 v120, v120, v52, v53
	v_max3_f32 v120, v120, v54, v55
	v_max3_f32 v120, v120, v56, v57
	v_max3_f32 v120, v120, v58, v59
	v_max3_f32 v120, v120, v60, v61
	v_max3_f32 v120, v120, v62, v63
	v_max3_f32 v120, v120, v64, v65
	s_nop 1
	v_max3_f32 v120, v120, v34, v35
	v_max3_f32 v120, v120, v36, v37
	v_max3_f32 v120, v120, v38, v39
	v_max3_f32 v120, v120, v40, v41
	v_max3_f32 v120, v120, v42, v43
	v_max3_f32 v120, v120, v44, v45
	v_max3_f32 v120, v120, v46, v47
	v_cndmask_b32_e32 v121, v209, v211, vcc
	v_max3_f32 v120, v120, v48, v49
	v_mov_b32_e32 v121, v120
	s_nop 1
	v_permlane32_swap_b32_e32 v121, v120
	v_max_f32_e32 v120, v120, v121
	v_mul_f32_e32 v120, 0x3e38aa3b, v120
	v_add_f32_e32 v121, 0x40c00000, v119
	v_cmp_gt_f32_e32 vcc, v120, v121
	s_cbranch_vccz .LBB0_520
	s_nop 0
	v_cndmask_b32_e32 v121, v119, v120, vcc
	v_sub_f32_e32 v119, v119, v121
	v_exp_f32_e32 v119, v119
	s_nop 0
	v_cndmask_b32_e32 v120, 1.0, v119, vcc
	v_mul_f32_e32 v117, v117, v120
	v_pk_mul_f32 v[32:33], v[32:33], v[120:121] op_sel_hi:[1,0]
	v_pk_mul_f32 v[30:31], v[30:31], v[120:121] op_sel_hi:[1,0]
	v_pk_mul_f32 v[28:29], v[28:29], v[120:121] op_sel_hi:[1,0]
	v_pk_mul_f32 v[26:27], v[26:27], v[120:121] op_sel_hi:[1,0]
	v_pk_mul_f32 v[24:25], v[24:25], v[120:121] op_sel_hi:[1,0]
	v_pk_mul_f32 v[22:23], v[22:23], v[120:121] op_sel_hi:[1,0]
	v_pk_mul_f32 v[20:21], v[20:21], v[120:121] op_sel_hi:[1,0]
	v_pk_mul_f32 v[18:19], v[18:19], v[120:121] op_sel_hi:[1,0]
	v_pk_mul_f32 v[16:17], v[16:17], v[120:121] op_sel_hi:[1,0]
	v_pk_mul_f32 v[14:15], v[14:15], v[120:121] op_sel_hi:[1,0]
	v_pk_mul_f32 v[12:13], v[12:13], v[120:121] op_sel_hi:[1,0]
	v_pk_mul_f32 v[10:11], v[10:11], v[120:121] op_sel_hi:[1,0]
	v_pk_mul_f32 v[8:9], v[8:9], v[120:121] op_sel_hi:[1,0]
	v_pk_mul_f32 v[6:7], v[6:7], v[120:121] op_sel_hi:[1,0]
	v_pk_mul_f32 v[4:5], v[4:5], v[120:121] op_sel_hi:[1,0]
	v_pk_mul_f32 v[2:3], v[2:3], v[120:121] op_sel_hi:[1,0]
	v_mov_b32_e32 v119, v121

.LBB0_608:
	s_and_b64 vcc, exec, s[2:3]
	s_cbranch_vccz .LBB0_614
	s_cmp_lg_u32 s76, 1
	s_cbranch_scc1 .LBB0_613
	v_add3_u32 v70, s37, v136, v139
	s_nop 6
	s_setprio 1
	ds_read_b128 v[34:37], v70
	ds_read_b128 v[38:41], v70 offset:16
	ds_read_b128 v[42:45], v70 offset:32
	ds_read_b128 v[46:49], v70 offset:48
	v_cmp_lt_i32_e32 vcc, v211, v210
	s_waitcnt lgkmcnt(3)
	v_mfma_f32_32x32x16_bf16 v[50:65], v[34:37], v[98:101], 0
	ds_read_b128 v[34:37], v70 offset:4608
	ds_read_b128 v[66:69], v70 offset:4624
	ds_read_b128 v[72:75], v70 offset:4640
	s_waitcnt lgkmcnt(5)
	v_mfma_f32_32x32x16_bf16 v[50:65], v[38:41], v[102:105], v[50:65]
	s_waitcnt lgkmcnt(4)
	v_mfma_f32_32x32x16_bf16 v[50:65], v[42:45], v[106:109], v[50:65]
	s_waitcnt lgkmcnt(3)
	v_mfma_f32_32x32x16_bf16 v[50:65], v[46:49], v[110:113], v[50:65]
	s_waitcnt lgkmcnt(2)
	v_mfma_f32_32x32x16_bf16 v[34:49], v[34:37], v[98:101], 0
	s_waitcnt lgkmcnt(1)
	v_mfma_f32_32x32x16_bf16 v[34:49], v[66:69], v[102:105], v[34:49]
	ds_read_b128 v[66:69], v70 offset:4656
	s_waitcnt lgkmcnt(1)
	v_mfma_f32_32x32x16_bf16 v[34:49], v[72:75], v[106:109], v[34:49]
	s_waitcnt lgkmcnt(0)
	v_mfma_f32_32x32x16_bf16 v[34:49], v[66:69], v[110:113], v[34:49]
	s_nop 1
	v_max3_f32 v66, v50, s85, v51
	v_max3_f32 v66, v66, v52, v53
	v_max3_f32 v66, v66, v54, v55
	v_max3_f32 v66, v66, v56, v57
	v_max3_f32 v66, v66, v58, v59
	v_max3_f32 v66, v66, v60, v61
	v_max3_f32 v66, v66, v62, v63
	v_max3_f32 v66, v66, v64, v65
	s_nop 1
	v_max3_f32 v66, v66, v34, v35
	v_max3_f32 v66, v66, v36, v37
	v_max3_f32 v66, v66, v38, v39
	v_max3_f32 v66, v66, v40, v41
	v_max3_f32 v66, v66, v42, v43
	v_max3_f32 v66, v66, v44, v45
	v_max3_f32 v66, v66, v46, v47
	v_cndmask_b32_e32 v67, v209, v211, vcc
	v_max3_f32 v66, v66, v48, v49
	v_mov_b32_e32 v67, v66
	s_nop 1
	v_permlane32_swap_b32_e32 v67, v66
	v_max_f32_e32 v66, v66, v67
	v_mul_f32_e32 v66, 0x3e38aa3b, v66
	v_add_f32_e32 v67, 0x40c00000, v152
	v_cmp_gt_f32_e32 vcc, v66, v67
	s_cbranch_vccz .LBB0_612
	s_nop 0
	v_cndmask_b32_e32 v67, v152, v66, vcc
	v_sub_f32_e32 v66, v152, v67
	v_exp_f32_e32 v66, v66
	v_mov_b32_e32 v152, v67
	v_cndmask_b32_e32 v66, 1.0, v66, vcc
	v_mul_f32_e32 v133, v133, v66
	v_pk_mul_f32 v[16:17], v[16:17], v[66:67] op_sel_hi:[1,0]
	v_pk_mul_f32 v[14:15], v[14:15], v[66:67] op_sel_hi:[1,0]
	v_pk_mul_f32 v[12:13], v[12:13], v[66:67] op_sel_hi:[1,0]
	v_pk_mul_f32 v[10:11], v[10:11], v[66:67] op_sel_hi:[1,0]
	v_pk_mul_f32 v[8:9], v[8:9], v[66:67] op_sel_hi:[1,0]
	v_pk_mul_f32 v[6:7], v[6:7], v[66:67] op_sel_hi:[1,0]
	v_pk_mul_f32 v[4:5], v[4:5], v[66:67] op_sel_hi:[1,0]
	v_pk_mul_f32 v[2:3], v[2:3], v[66:67] op_sel_hi:[1,0]
	v_pk_mul_f32 v[32:33], v[32:33], v[66:67] op_sel_hi:[1,0]
	v_pk_mul_f32 v[30:31], v[30:31], v[66:67] op_sel_hi:[1,0]
	v_pk_mul_f32 v[28:29], v[28:29], v[66:67] op_sel_hi:[1,0]
	v_pk_mul_f32 v[26:27], v[26:27], v[66:67] op_sel_hi:[1,0]
	v_pk_mul_f32 v[24:25], v[24:25], v[66:67] op_sel_hi:[1,0]
	v_pk_mul_f32 v[22:23], v[22:23], v[66:67] op_sel_hi:[1,0]
	v_pk_mul_f32 v[20:21], v[20:21], v[66:67] op_sel_hi:[1,0]
	v_pk_mul_f32 v[18:19], v[18:19], v[66:67] op_sel_hi:[1,0]

.LBB0_654:
	s_and_b64 vcc, exec, s[2:3]
	s_cbranch_vccz .LBB0_660
	s_cmp_lg_u32 s76, 1
	s_cbranch_scc1 .LBB0_659
	v_add3_u32 v70, s37, v136, v139
	s_nop 6
	s_setprio 1
	ds_read_b128 v[34:37], v70
	ds_read_b128 v[38:41], v70 offset:16
	ds_read_b128 v[42:45], v70 offset:32
	ds_read_b128 v[46:49], v70 offset:48
	v_cmp_lt_i32_e32 vcc, v211, v210
	s_waitcnt lgkmcnt(3)
	v_mfma_f32_32x32x16_bf16 v[50:65], v[34:37], v[98:101], 0
	ds_read_b128 v[34:37], v70 offset:4608
	ds_read_b128 v[66:69], v70 offset:4624
	ds_read_b128 v[72:75], v70 offset:4640
	ds_read_b128 v[76:79], v70 offset:4656
	s_waitcnt lgkmcnt(6)
	v_mfma_f32_32x32x16_bf16 v[50:65], v[38:41], v[102:105], v[50:65]
	s_waitcnt lgkmcnt(5)
	v_mfma_f32_32x32x16_bf16 v[50:65], v[42:45], v[106:109], v[50:65]
	s_waitcnt lgkmcnt(4)
	v_mfma_f32_32x32x16_bf16 v[50:65], v[46:49], v[110:113], v[50:65]
	s_waitcnt lgkmcnt(3)
	v_mfma_f32_32x32x16_bf16 v[34:49], v[34:37], v[98:101], 0
	s_waitcnt lgkmcnt(2)
	v_mfma_f32_32x32x16_bf16 v[34:49], v[66:69], v[102:105], v[34:49]
	s_waitcnt lgkmcnt(1)
	v_mfma_f32_32x32x16_bf16 v[34:49], v[72:75], v[106:109], v[34:49]
	s_waitcnt lgkmcnt(0)
	v_mfma_f32_32x32x16_bf16 v[34:49], v[76:79], v[110:113], v[34:49]
	s_nop 1
	v_max3_f32 v66, v50, s85, v51
	v_max3_f32 v66, v66, v52, v53
	v_max3_f32 v66, v66, v54, v55
	v_max3_f32 v66, v66, v56, v57
	v_max3_f32 v66, v66, v58, v59
	v_max3_f32 v66, v66, v60, v61
	v_max3_f32 v66, v66, v62, v63
	v_max3_f32 v66, v66, v64, v65
	s_nop 1
	v_max3_f32 v66, v66, v34, v35
	v_max3_f32 v66, v66, v36, v37
	v_max3_f32 v66, v66, v38, v39
	v_max3_f32 v66, v66, v40, v41
	v_max3_f32 v66, v66, v42, v43
	v_max3_f32 v66, v66, v44, v45
	v_max3_f32 v66, v66, v46, v47
	v_cndmask_b32_e32 v67, v209, v211, vcc
	v_max3_f32 v66, v66, v48, v49
	v_mov_b32_e32 v67, v66
	s_nop 1
	v_permlane32_swap_b32_e32 v67, v66
	v_max_f32_e32 v66, v66, v67
	v_mul_f32_e32 v66, 0x3e38aa3b, v66
	v_add_f32_e32 v67, 0x40c00000, v152
	v_cmp_gt_f32_e32 vcc, v66, v67
	s_cbranch_vccz .LBB0_658
	s_nop 0
	v_cndmask_b32_e32 v67, v152, v66, vcc
	v_sub_f32_e32 v66, v152, v67
	v_exp_f32_e32 v66, v66
	v_mov_b32_e32 v152, v67
	v_cndmask_b32_e32 v66, 1.0, v66, vcc
	v_mul_f32_e32 v133, v133, v66
	v_pk_mul_f32 v[16:17], v[16:17], v[66:67] op_sel_hi:[1,0]
	v_pk_mul_f32 v[14:15], v[14:15], v[66:67] op_sel_hi:[1,0]
	v_pk_mul_f32 v[12:13], v[12:13], v[66:67] op_sel_hi:[1,0]
	v_pk_mul_f32 v[10:11], v[10:11], v[66:67] op_sel_hi:[1,0]
	v_pk_mul_f32 v[8:9], v[8:9], v[66:67] op_sel_hi:[1,0]
	v_pk_mul_f32 v[6:7], v[6:7], v[66:67] op_sel_hi:[1,0]
	v_pk_mul_f32 v[4:5], v[4:5], v[66:67] op_sel_hi:[1,0]
	v_pk_mul_f32 v[2:3], v[2:3], v[66:67] op_sel_hi:[1,0]
	v_pk_mul_f32 v[32:33], v[32:33], v[66:67] op_sel_hi:[1,0]
	v_pk_mul_f32 v[30:31], v[30:31], v[66:67] op_sel_hi:[1,0]
	v_pk_mul_f32 v[28:29], v[28:29], v[66:67] op_sel_hi:[1,0]
	v_pk_mul_f32 v[26:27], v[26:27], v[66:67] op_sel_hi:[1,0]
	v_pk_mul_f32 v[24:25], v[24:25], v[66:67] op_sel_hi:[1,0]
	v_pk_mul_f32 v[22:23], v[22:23], v[66:67] op_sel_hi:[1,0]
	v_pk_mul_f32 v[20:21], v[20:21], v[66:67] op_sel_hi:[1,0]
	v_pk_mul_f32 v[18:19], v[18:19], v[66:67] op_sel_hi:[1,0]

.LBB0_762:
	s_and_b64 vcc, exec, s[2:3]
	s_cbranch_vccz .LBB0_768
	s_cmp_lg_u32 s16, 1
	s_cbranch_scc1 .LBB0_767
	v_add3_u32 v70, s76, v132, v137
	s_setprio 1
	ds_read_b128 v[34:37], v70
	ds_read_b128 v[38:41], v70 offset:16
	ds_read_b128 v[42:45], v70 offset:32
	ds_read_b128 v[46:49], v70 offset:48
	v_cmp_lt_i32_e32 vcc, v211, v210
	s_waitcnt lgkmcnt(3)
	v_mfma_f32_32x32x16_bf16 v[50:65], v[34:37], v[98:101], 0
	ds_read_b128 v[34:37], v70 offset:4608
	ds_read_b128 v[66:69], v70 offset:4624
	ds_read_b128 v[72:75], v70 offset:4640
	s_waitcnt lgkmcnt(5)
	v_mfma_f32_32x32x16_bf16 v[50:65], v[38:41], v[102:105], v[50:65]
	s_waitcnt lgkmcnt(4)
	v_mfma_f32_32x32x16_bf16 v[50:65], v[42:45], v[106:109], v[50:65]
	s_waitcnt lgkmcnt(3)
	v_mfma_f32_32x32x16_bf16 v[50:65], v[46:49], v[110:113], v[50:65]
	s_waitcnt lgkmcnt(2)
	v_mfma_f32_32x32x16_bf16 v[34:49], v[34:37], v[98:101], 0
	s_waitcnt lgkmcnt(1)
	v_mfma_f32_32x32x16_bf16 v[34:49], v[66:69], v[102:105], v[34:49]
	ds_read_b128 v[66:69], v70 offset:4656
	s_waitcnt lgkmcnt(1)
	v_mfma_f32_32x32x16_bf16 v[34:49], v[72:75], v[106:109], v[34:49]
	s_waitcnt lgkmcnt(0)
	v_mfma_f32_32x32x16_bf16 v[34:49], v[66:69], v[110:113], v[34:49]
	s_nop 1
	v_max3_f32 v66, v50, s85, v51
	v_max3_f32 v66, v66, v52, v53
	v_max3_f32 v66, v66, v54, v55
	v_max3_f32 v66, v66, v56, v57
	v_max3_f32 v66, v66, v58, v59
	v_max3_f32 v66, v66, v60, v61
	v_max3_f32 v66, v66, v62, v63
	v_max3_f32 v66, v66, v64, v65
	s_nop 1
	v_max3_f32 v66, v66, v34, v35
	v_max3_f32 v66, v66, v36, v37
	v_max3_f32 v66, v66, v38, v39
	v_max3_f32 v66, v66, v40, v41
	v_max3_f32 v66, v66, v42, v43
	v_max3_f32 v66, v66, v44, v45
	v_max3_f32 v66, v66, v46, v47
	v_cndmask_b32_e32 v67, v209, v211, vcc
	v_max3_f32 v66, v66, v48, v49
	v_mov_b32_e32 v67, v66
	s_nop 1
	v_permlane32_swap_b32_e32 v67, v66
	v_max_f32_e32 v66, v66, v67
	v_mul_f32_e32 v66, 0x3e38aa3b, v66
	v_add_f32_e32 v67, 0x40c00000, v152
	v_cmp_gt_f32_e32 vcc, v66, v67
	s_cbranch_vccz .LBB0_766
	s_nop 0
	v_cndmask_b32_e32 v67, v152, v66, vcc
	v_sub_f32_e32 v66, v152, v67
	v_exp_f32_e32 v66, v66
	v_mov_b32_e32 v152, v67
	v_cndmask_b32_e32 v66, 1.0, v66, vcc
	v_mul_f32_e32 v151, v151, v66
	v_pk_mul_f32 v[16:17], v[16:17], v[66:67] op_sel_hi:[1,0]
	v_pk_mul_f32 v[14:15], v[14:15], v[66:67] op_sel_hi:[1,0]
	v_pk_mul_f32 v[12:13], v[12:13], v[66:67] op_sel_hi:[1,0]
	v_pk_mul_f32 v[10:11], v[10:11], v[66:67] op_sel_hi:[1,0]
	v_pk_mul_f32 v[8:9], v[8:9], v[66:67] op_sel_hi:[1,0]
	v_pk_mul_f32 v[6:7], v[6:7], v[66:67] op_sel_hi:[1,0]
	v_pk_mul_f32 v[4:5], v[4:5], v[66:67] op_sel_hi:[1,0]
	v_pk_mul_f32 v[2:3], v[2:3], v[66:67] op_sel_hi:[1,0]
	v_pk_mul_f32 v[32:33], v[32:33], v[66:67] op_sel_hi:[1,0]
	v_pk_mul_f32 v[30:31], v[30:31], v[66:67] op_sel_hi:[1,0]
	v_pk_mul_f32 v[28:29], v[28:29], v[66:67] op_sel_hi:[1,0]
	v_pk_mul_f32 v[26:27], v[26:27], v[66:67] op_sel_hi:[1,0]
	v_pk_mul_f32 v[24:25], v[24:25], v[66:67] op_sel_hi:[1,0]
	v_pk_mul_f32 v[22:23], v[22:23], v[66:67] op_sel_hi:[1,0]
	v_pk_mul_f32 v[20:21], v[20:21], v[66:67] op_sel_hi:[1,0]
	v_pk_mul_f32 v[18:19], v[18:19], v[66:67] op_sel_hi:[1,0]

.LBB0_883:
	s_add_i32 s39, s41, 1
	v_mov_b32_e32 v36, v2
	s_waitcnt vmcnt(3)
	v_mov_b64_e32 v[2:3], v[50:51]
	s_cmp_lt_u32 s41, s15
	v_mov_b64_e32 v[4:5], v[52:53]
	s_cselect_b32 s41, s2, 0
	v_or_b32_e32 v6, s41, v93
	v_ashrrev_i32_e32 v7, 31, v6
	v_lshlrev_b64 v[6:7], 7, v[6:7]
	s_waitcnt vmcnt(0)
	v_mov_b64_e32 v[24:25], v[62:63]
	v_mov_b64_e32 v[28:29], v[58:59]
	v_mov_b64_e32 v[32:33], v[54:55]
	v_lshl_add_u64 v[6:7], v[82:83], 0, v[6:7]
	v_mov_b64_e32 v[26:27], v[64:65]
	v_mov_b64_e32 v[30:31], v[60:61]
	v_mov_b64_e32 v[34:35], v[56:57]
	global_load_dwordx4 v[50:53], v[6:7], off
	global_load_dwordx4 v[54:57], v[6:7], off offset:16
	global_load_dwordx4 v[58:61], v[6:7], off offset:32
	global_load_dwordx4 v[62:65], v[6:7], off offset:48
	s_setprio 0
	v_mfma_f32_32x32x16_bf16 v[2:17], v[2:5], v[130:133], 0
	s_add_i32 s2, s2, 32
	s_mov_b32 s41, s39
	v_mfma_f32_32x32x16_bf16 v[2:17], v[32:35], v[134:137], v[2:17]
	v_mfma_f32_32x32x16_bf16 v[2:17], v[28:31], v[138:141], v[2:17]
	v_mfma_f32_32x32x16_bf16 v[2:17], v[24:27], v[142:145], v[2:17]
	v_add_u32_e32 v24, s3, v20
	v_cmp_le_i32_e32 vcc, v24, v22
	v_add_u32_e32 v25, 16, v24
	v_add_u32_e32 v26, 32, v24
	s_addk_i32 s3, 0x200
	s_cmp_eq_u32 s38, s3
	s_nop 5
	v_mul_f32_e32 v2, 0x3e38aa3b, v2
	v_cndmask_b32_e32 v2, v220, v2, vcc
	v_mul_f32_e32 v3, 0x3e38aa3b, v3
	v_cmp_le_i32_e32 vcc, v25, v22
	v_mul_f32_e32 v4, 0x3e38aa3b, v4
	v_mul_f32_e32 v5, 0x3e38aa3b, v5
	v_cndmask_b32_e32 v3, v220, v3, vcc
	v_cmp_le_i32_e32 vcc, v26, v22
	v_add_u32_e32 v26, 48, v24
	v_mul_f32_e32 v6, 0x3e38aa3b, v6
	v_cndmask_b32_e32 v4, v220, v4, vcc
	v_cmp_le_i32_e32 vcc, v26, v22
	v_add_u32_e32 v26, 64, v24
	v_mul_f32_e32 v7, 0x3e38aa3b, v7
	v_cndmask_b32_e32 v5, v220, v5, vcc
	v_cmp_le_i32_e32 vcc, v26, v22
	v_add_u32_e32 v26, 0x50, v24
	v_mul_f32_e32 v8, 0x3e38aa3b, v8
	v_cndmask_b32_e32 v6, v220, v6, vcc
	v_cmp_le_i32_e32 vcc, v26, v22
	v_add_u32_e32 v26, 0x60, v24
	v_mul_f32_e32 v9, 0x3e38aa3b, v9
	v_cndmask_b32_e32 v7, v220, v7, vcc
	v_cmp_le_i32_e32 vcc, v26, v22
	v_add_u32_e32 v26, 0x70, v24
	v_mul_f32_e32 v10, 0x3e38aa3b, v10
	v_cndmask_b32_e32 v8, v220, v8, vcc
	v_cmp_le_i32_e32 vcc, v26, v22
	v_add_u32_e32 v26, 0x100, v24
	v_mul_f32_e32 v11, 0x3e38aa3b, v11
	v_cndmask_b32_e32 v9, v220, v9, vcc
	v_cmp_le_i32_e32 vcc, v26, v22
	v_add_u32_e32 v26, 0x110, v24
	v_max3_f32 v25, v2, s85, v3
	v_cndmask_b32_e32 v10, v220, v10, vcc
	v_cmp_le_i32_e32 vcc, v26, v22
	v_add_u32_e32 v26, 0x120, v24
	v_mul_f32_e32 v12, 0x3e38aa3b, v12
	v_cndmask_b32_e32 v11, v220, v11, vcc
	v_cmp_le_i32_e32 vcc, v26, v22
	v_add_u32_e32 v26, 0x130, v24
	v_max3_f32 v25, v25, v4, v5
	v_cndmask_b32_e32 v12, v220, v12, vcc
	v_mul_f32_e32 v13, 0x3e38aa3b, v13
	v_cmp_le_i32_e32 vcc, v26, v22
	v_add_u32_e32 v26, 0x140, v24
	v_max3_f32 v25, v25, v6, v7
	v_cndmask_b32_e32 v13, v220, v13, vcc
	v_mul_f32_e32 v14, 0x3e38aa3b, v14
	v_cmp_le_i32_e32 vcc, v26, v22
	v_add_u32_e32 v26, 0x150, v24
	v_max3_f32 v25, v25, v8, v9
	v_cndmask_b32_e32 v14, v220, v14, vcc
	v_mul_f32_e32 v15, 0x3e38aa3b, v15
	v_cmp_le_i32_e32 vcc, v26, v22
	v_add_u32_e32 v26, 0x160, v24
	v_max3_f32 v25, v25, v10, v11
	v_cndmask_b32_e32 v15, v220, v15, vcc
	v_mul_f32_e32 v16, 0x3e38aa3b, v16
	v_cmp_le_i32_e32 vcc, v26, v22
	v_add_u32_e32 v24, 0x170, v24
	v_max3_f32 v25, v25, v12, v13
	v_cndmask_b32_e32 v16, v220, v16, vcc
	v_mul_f32_e32 v17, 0x3e38aa3b, v17
	v_cmp_le_i32_e32 vcc, v24, v22
	v_max3_f32 v25, v25, v14, v15
	s_nop 0
	v_cndmask_b32_e32 v17, v220, v17, vcc
	v_max3_f32 v24, v25, v16, v17
	v_mov_b32_e32 v25, v24
	s_nop 1
	v_permlane32_swap_b32_e32 v25, v24
	s_waitcnt lgkmcnt(0)
	v_max3_f32 v24, v23, v24, v25
	v_cmp_neq_f32_e32 vcc, s85, v24
	s_nop 1
	v_cndmask_b32_e32 v96, 0, v24, vcc
	v_sub_f32_e32 v2, v2, v96
	v_exp_f32_e32 v2, v2
	v_sub_f32_e32 v3, v3, v96
	v_exp_f32_e32 v3, v3
	v_sub_f32_e32 v23, v23, v96
	v_add_f32_e32 v2, 0, v2
	v_add_f32_e32 v2, v3, v2
	v_sub_f32_e32 v3, v4, v96
	v_exp_f32_e32 v3, v3
	s_nop 0
	v_add_f32_e32 v2, v3, v2
	v_sub_f32_e32 v3, v5, v96
	v_exp_f32_e32 v3, v3
	s_nop 0
	v_add_f32_e32 v2, v3, v2
	v_sub_f32_e32 v3, v6, v96
	v_exp_f32_e32 v3, v3
	s_nop 0
	v_add_f32_e32 v2, v3, v2
	v_sub_f32_e32 v3, v7, v96
	v_exp_f32_e32 v3, v3
	s_nop 0
	v_add_f32_e32 v2, v3, v2
	v_sub_f32_e32 v3, v8, v96
	v_exp_f32_e32 v3, v3
	s_nop 0
	v_add_f32_e32 v2, v3, v2
	v_sub_f32_e32 v3, v9, v96
	v_exp_f32_e32 v3, v3
	s_nop 0
	v_add_f32_e32 v2, v3, v2
	v_sub_f32_e32 v3, v10, v96
	v_exp_f32_e32 v3, v3
	s_nop 0
	v_add_f32_e32 v2, v3, v2
	v_sub_f32_e32 v3, v11, v96
	v_exp_f32_e32 v3, v3
	s_nop 0
	v_add_f32_e32 v2, v3, v2
	v_sub_f32_e32 v3, v12, v96
	v_exp_f32_e32 v3, v3
	s_nop 0
	v_add_f32_e32 v2, v3, v2
	v_sub_f32_e32 v3, v13, v96
	v_exp_f32_e32 v3, v3
	s_nop 0
	v_add_f32_e32 v2, v3, v2
	v_sub_f32_e32 v3, v14, v96
	v_exp_f32_e32 v3, v3
	s_nop 0
	v_add_f32_e32 v2, v3, v2
	v_sub_f32_e32 v3, v15, v96
	v_exp_f32_e32 v3, v3
	s_nop 0
	v_add_f32_e32 v2, v3, v2
	v_sub_f32_e32 v3, v16, v96
	v_exp_f32_e32 v3, v3
	s_nop 0
	v_add_f32_e32 v2, v3, v2
	v_sub_f32_e32 v3, v17, v96
	v_exp_f32_e32 v3, v3
	s_nop 0
	v_add_f32_e32 v2, v3, v2
	v_exp_f32_e32 v3, v23
	v_mov_b32_e32 v23, v24
	v_fmac_f32_e32 v2, v36, v3
	s_cbranch_scc0 .LBB0_883
	ds_bpermute_b32 v3, v167, v2
	v_lshlrev_b32_e32 v166, 3, v21
	v_add_u32_e32 v98, 0x18f, v20
	v_lshl_or_b32 v84, v92, 8, v223
	v_mov_b32_e32 v85, v1
	s_waitcnt lgkmcnt(0)
	v_add_f32_e32 v3, v2, v3
	v_div_scale_f32 v4, s[2:3], v3, v3, 1.0
	v_rcp_f32_e32 v5, v4
	v_div_scale_f32 v6, vcc, 1.0, v3, 1.0
	s_add_u32 s2, s18, s22
	v_fma_f32 v7, -v4, v5, 1.0
	v_fmac_f32_e32 v5, v7, v5
	v_mul_f32_e32 v7, v6, v5
	v_fma_f32 v8, -v4, v7, v6
	v_fmac_f32_e32 v7, v8, v5
	v_fma_f32 v4, -v4, v7, v6
	v_div_fmas_f32 v4, v4, v5, v7
	v_div_fixup_f32 v4, v4, v3, 1.0
	v_cmp_lt_f32_e32 vcc, 0, v3
	v_lshlrev_b32_e32 v3, 12, v18
	v_mov_b32_e32 v2, 0
	v_cndmask_b32_e32 v97, 0, v4, vcc
	v_lshlrev_b32_e32 v4, 7, v91
	v_or3_b32 v99, v3, v4, v166
	v_and_b32_e32 v4, 16, v19
	v_mov_b32_e32 v5, v1
	s_addc_u32 s3, s19, s23
	v_lshl_add_u64 v[86:87], s[2:3], 0, v[4:5]
	v_lshlrev_b32_e32 v88, 8, v91
	v_mov_b32_e32 v89, v1
	s_mov_b32 s22, 0
	v_mov_b32_e32 v3, v2
	v_mov_b32_e32 v4, v2
	v_mov_b32_e32 v5, v2
	v_mov_b32_e32 v6, v2
	v_mov_b32_e32 v7, v2
	v_mov_b32_e32 v8, v2
	v_mov_b32_e32 v9, v2
	v_mov_b32_e32 v10, v2
	v_mov_b32_e32 v11, v2
	v_mov_b32_e32 v12, v2
	v_mov_b32_e32 v13, v2
	v_mov_b32_e32 v14, v2
	v_mov_b32_e32 v15, v2
	v_mov_b32_e32 v16, v2
	v_mov_b32_e32 v17, v2
	v_mov_b32_e32 v18, v2
	v_mov_b32_e32 v19, v2
	v_mov_b32_e32 v20, v2
	v_mov_b32_e32 v21, v2
	v_mov_b32_e32 v22, v2
	v_mov_b32_e32 v23, v2
	v_mov_b32_e32 v24, v2
	v_mov_b32_e32 v25, v2
	v_mov_b32_e32 v26, v2
	v_mov_b32_e32 v27, v2
	v_mov_b32_e32 v28, v2
	v_mov_b32_e32 v29, v2
	v_mov_b32_e32 v30, v2
	v_mov_b32_e32 v31, v2
	v_mov_b32_e32 v32, v2
	v_mov_b32_e32 v33, v2
	s_branch .LBB0_886

.LBB0_934:
	s_andn2_b64 vcc, exec, s[2:3]
	s_cbranch_vccnz .LBB0_940
	s_cmp_lg_u32 s76, 1
	s_cbranch_scc1 .LBB0_939
	v_add3_u32 v102, s23, v170, v173
	s_setprio 1
	ds_read_b128 v[66:69], v102
	ds_read_b128 v[70:73], v102 offset:16
	ds_read_b128 v[74:77], v102 offset:32
	ds_read_b128 v[78:81], v102 offset:48
	s_waitcnt lgkmcnt(3)
	v_mfma_f32_32x32x16_bf16 v[82:97], v[66:69], v[130:133], 0
	ds_read_b128 v[66:69], v102 offset:4608
	ds_read_b128 v[98:101], v102 offset:4624
	ds_read_b128 v[104:107], v102 offset:4640
	s_waitcnt lgkmcnt(5)
	v_mfma_f32_32x32x16_bf16 v[82:97], v[70:73], v[134:137], v[82:97]
	s_waitcnt lgkmcnt(4)
	v_mfma_f32_32x32x16_bf16 v[82:97], v[74:77], v[138:141], v[82:97]
	s_waitcnt lgkmcnt(3)
	v_mfma_f32_32x32x16_bf16 v[82:97], v[78:81], v[142:145], v[82:97]
	s_waitcnt lgkmcnt(2)
	v_mfma_f32_32x32x16_bf16 v[66:81], v[66:69], v[130:133], 0
	s_waitcnt lgkmcnt(1)
	v_mfma_f32_32x32x16_bf16 v[66:81], v[98:101], v[134:137], v[66:81]
	ds_read_b128 v[98:101], v102 offset:4656
	s_waitcnt lgkmcnt(1)
	v_mfma_f32_32x32x16_bf16 v[66:81], v[104:107], v[138:141], v[66:81]
	s_waitcnt lgkmcnt(0)
	v_mfma_f32_32x32x16_bf16 v[66:81], v[98:101], v[142:145], v[66:81]
	s_nop 1
	v_max3_f32 v98, v82, s85, v83
	v_max3_f32 v98, v98, v84, v85
	v_max3_f32 v98, v98, v86, v87
	v_max3_f32 v98, v98, v88, v89
	v_max3_f32 v98, v98, v90, v91
	v_max3_f32 v98, v98, v92, v93
	v_max3_f32 v98, v98, v94, v95
	v_max3_f32 v98, v98, v96, v97
	s_nop 1
	v_max3_f32 v98, v98, v66, v67
	v_max3_f32 v98, v98, v68, v69
	v_max3_f32 v98, v98, v70, v71
	v_max3_f32 v98, v98, v72, v73
	v_max3_f32 v98, v98, v74, v75
	v_max3_f32 v98, v98, v76, v77
	v_max3_f32 v98, v98, v78, v79
	v_max3_f32 v98, v98, v80, v81
	v_mov_b32_e32 v99, v98
	s_nop 1
	v_permlane32_swap_b32_e32 v99, v98
	s_waitcnt lgkmcnt(0)
	v_max_f32_e32 v99, v99, v99
	v_max_f32_e32 v98, v98, v99
	v_mul_f32_e32 v98, 0x3e38aa3b, v98
	v_add_f32_e32 v99, 0x40c00000, v189
	v_cmp_gt_f32_e32 vcc, v98, v99
	s_cbranch_vccz .LBB0_938
	s_nop 0
	v_cndmask_b32_e32 v99, v189, v98, vcc
	v_sub_f32_e32 v98, v189, v99
	v_exp_f32_e32 v98, v98
	v_mov_b32_e32 v189, v99
	v_cndmask_b32_e32 v98, 1.0, v98, vcc
	v_mul_f32_e32 v188, v188, v98
	v_pk_mul_f32 v[48:49], v[48:49], v[98:99] op_sel_hi:[1,0]
	v_pk_mul_f32 v[46:47], v[46:47], v[98:99] op_sel_hi:[1,0]
	v_pk_mul_f32 v[44:45], v[44:45], v[98:99] op_sel_hi:[1,0]
	v_pk_mul_f32 v[42:43], v[42:43], v[98:99] op_sel_hi:[1,0]
	v_pk_mul_f32 v[40:41], v[40:41], v[98:99] op_sel_hi:[1,0]
	v_pk_mul_f32 v[38:39], v[38:39], v[98:99] op_sel_hi:[1,0]
	v_pk_mul_f32 v[36:37], v[36:37], v[98:99] op_sel_hi:[1,0]
	v_pk_mul_f32 v[34:35], v[34:35], v[98:99] op_sel_hi:[1,0]
	v_pk_mul_f32 v[64:65], v[64:65], v[98:99] op_sel_hi:[1,0]
	v_pk_mul_f32 v[62:63], v[62:63], v[98:99] op_sel_hi:[1,0]
	v_pk_mul_f32 v[60:61], v[60:61], v[98:99] op_sel_hi:[1,0]
	v_pk_mul_f32 v[58:59], v[58:59], v[98:99] op_sel_hi:[1,0]
	v_pk_mul_f32 v[56:57], v[56:57], v[98:99] op_sel_hi:[1,0]
	v_pk_mul_f32 v[54:55], v[54:55], v[98:99] op_sel_hi:[1,0]
	v_pk_mul_f32 v[52:53], v[52:53], v[98:99] op_sel_hi:[1,0]
	v_pk_mul_f32 v[50:51], v[50:51], v[98:99] op_sel_hi:[1,0]
